# P1+P8 K-loops rotated; counter bump and exit test moved behind the first load section's LDS reads (exit stub drains them); no GEMM setprio; merged waits
# baseline (speedup 1.0000x reference)
.LBB0_327:
	s_ashr_i32 s23, s22, 31
	s_lshl_b64 s[24:25], s[22:23], 19
	s_add_u32 s24, s72, s24
	s_addc_u32 s25, s73, s25
	s_and_b64 s[26:27], s[6:7], exec
	s_cselect_b32 s23, s25, s47
	s_cselect_b32 s56, s24, s46
	s_ashr_i32 s21, s20, 31
	s_lshl_b64 s[26:27], s[20:21], 19
	s_add_u32 s26, s0, s26
	s_addc_u32 s27, s1, s27
	s_and_b64 s[48:49], s[6:7], exec
	s_cselect_b32 s57, s27, s31
	s_cselect_b32 s58, s26, s30
	s_lshl_b32 s21, s28, 8
	v_add_u32_e32 v6, s21, v227
	s_add_u32 s28, s46, 0x3ff80
	v_ashrrev_i32_e32 v7, 31, v6
	s_addc_u32 s29, s47, 0
	v_lshl_add_u64 v[214:215], v[6:7], 4, s[16:17]
	s_add_u32 s59, s30, 0
	v_mov_b32_e32 v6, 0
	s_addc_u32 s60, s31, 0
	s_mov_b32 s61, -4
	v_mov_b32_e32 v7, v6
	v_mov_b32_e32 v8, v6
	v_mov_b32_e32 v9, v6
	v_mov_b32_e32 v14, v6
	v_mov_b32_e32 v15, v6
	v_mov_b32_e32 v16, v6
	v_mov_b32_e32 v17, v6
	v_mov_b32_e32 v22, v6
	v_mov_b32_e32 v23, v6
	v_mov_b32_e32 v24, v6
	v_mov_b32_e32 v25, v6
	v_mov_b32_e32 v30, v6
	v_mov_b32_e32 v31, v6
	v_mov_b32_e32 v32, v6
	v_mov_b32_e32 v33, v6
	v_mov_b32_e32 v38, v6
	v_mov_b32_e32 v39, v6
	v_mov_b32_e32 v40, v6
	v_mov_b32_e32 v41, v6
	v_mov_b32_e32 v46, v6
	v_mov_b32_e32 v47, v6
	v_mov_b32_e32 v48, v6
	v_mov_b32_e32 v49, v6
	v_mov_b32_e32 v54, v6
	v_mov_b32_e32 v55, v6
	v_mov_b32_e32 v56, v6
	v_mov_b32_e32 v57, v6
	v_mov_b32_e32 v62, v6
	v_mov_b32_e32 v63, v6
	v_mov_b32_e32 v64, v6
	v_mov_b32_e32 v65, v6
	v_mov_b32_e32 v10, v6
	v_mov_b32_e32 v11, v6
	v_mov_b32_e32 v12, v6
	v_mov_b32_e32 v13, v6
	v_mov_b32_e32 v18, v6
	v_mov_b32_e32 v19, v6
	v_mov_b32_e32 v20, v6
	v_mov_b32_e32 v21, v6
	v_mov_b32_e32 v26, v6
	v_mov_b32_e32 v27, v6
	v_mov_b32_e32 v28, v6
	v_mov_b32_e32 v29, v6
	v_mov_b32_e32 v34, v6
	v_mov_b32_e32 v35, v6
	v_mov_b32_e32 v36, v6
	v_mov_b32_e32 v37, v6
	v_mov_b32_e32 v42, v6
	v_mov_b32_e32 v43, v6
	v_mov_b32_e32 v44, v6
	v_mov_b32_e32 v45, v6
	v_mov_b32_e32 v50, v6
	v_mov_b32_e32 v51, v6
	v_mov_b32_e32 v52, v6
	v_mov_b32_e32 v53, v6
	v_mov_b32_e32 v58, v6
	v_mov_b32_e32 v59, v6
	v_mov_b32_e32 v60, v6
	v_mov_b32_e32 v61, v6
	v_mov_b32_e32 v66, v6
	v_mov_b32_e32 v67, v6
	v_mov_b32_e32 v68, v6
	v_mov_b32_e32 v69, v6
	v_mov_b32_e32 v70, v6
	v_mov_b32_e32 v71, v6
	v_mov_b32_e32 v72, v6
	v_mov_b32_e32 v73, v6
	v_mov_b32_e32 v78, v6
	v_mov_b32_e32 v79, v6
	v_mov_b32_e32 v80, v6
	v_mov_b32_e32 v81, v6
	v_mov_b32_e32 v86, v6
	v_mov_b32_e32 v87, v6
	v_mov_b32_e32 v88, v6
	v_mov_b32_e32 v89, v6
	v_mov_b32_e32 v94, v6
	v_mov_b32_e32 v95, v6
	v_mov_b32_e32 v96, v6
	v_mov_b32_e32 v97, v6
	v_mov_b32_e32 v102, v6
	v_mov_b32_e32 v103, v6
	v_mov_b32_e32 v104, v6
	v_mov_b32_e32 v105, v6
	v_mov_b32_e32 v110, v6
	v_mov_b32_e32 v111, v6
	v_mov_b32_e32 v112, v6
	v_mov_b32_e32 v113, v6
	v_mov_b32_e32 v118, v6
	v_mov_b32_e32 v119, v6
	v_mov_b32_e32 v120, v6
	v_mov_b32_e32 v121, v6
	v_mov_b32_e32 v126, v6
	v_mov_b32_e32 v127, v6
	v_mov_b32_e32 v128, v6
	v_mov_b32_e32 v129, v6
	v_mov_b32_e32 v74, v6
	v_mov_b32_e32 v75, v6
	v_mov_b32_e32 v76, v6
	v_mov_b32_e32 v77, v6
	v_mov_b32_e32 v82, v6
	v_mov_b32_e32 v83, v6
	v_mov_b32_e32 v84, v6
	v_mov_b32_e32 v85, v6
	v_mov_b32_e32 v90, v6
	v_mov_b32_e32 v91, v6
	v_mov_b32_e32 v92, v6
	v_mov_b32_e32 v93, v6
	v_mov_b32_e32 v98, v6
	v_mov_b32_e32 v99, v6
	v_mov_b32_e32 v100, v6
	v_mov_b32_e32 v101, v6
	v_mov_b32_e32 v106, v6
	v_mov_b32_e32 v107, v6
	v_mov_b32_e32 v108, v6
	v_mov_b32_e32 v109, v6
	v_mov_b32_e32 v114, v6
	v_mov_b32_e32 v115, v6
	v_mov_b32_e32 v116, v6
	v_mov_b32_e32 v117, v6
	v_mov_b32_e32 v122, v6
	v_mov_b32_e32 v123, v6
	v_mov_b32_e32 v124, v6
	v_mov_b32_e32 v125, v6
	v_mov_b32_e32 v130, v6
	v_mov_b32_e32 v131, v6
	v_mov_b32_e32 v132, v6
	v_mov_b32_e32 v133, v6
	s_branch .LBB0_330

.LBB0_330:
	v_add_u32_e32 v146, s53, v225
	v_add_u32_e32 v162, s54, v225
	ds_read_b128 v[134:137], v146
	ds_read_b128 v[138:141], v146 offset:1024
	ds_read_b128 v[142:145], v146 offset:2048
	ds_read_b128 v[146:149], v146 offset:3072
	ds_read_b128 v[150:153], v162
	ds_read_b128 v[154:157], v162 offset:1024
	ds_read_b128 v[158:161], v162 offset:2048
	ds_read_b128 v[162:165], v162 offset:3072
	ds_read_b128 v[166:169], v229
	ds_read_b128 v[170:173], v229 offset:1024
	ds_read_b128 v[174:177], v229 offset:2048
	ds_read_b128 v[178:181], v229 offset:3072
	ds_read_b128 v[182:185], v229 offset:4096
	ds_read_b128 v[186:189], v229 offset:5120
	ds_read_b128 v[190:193], v229 offset:6144
	ds_read_b128 v[194:197], v229 offset:7168
	s_add_i32 s61, s61, 2
	s_cmp_gt_i32 s61, 13
	s_cbranch_scc1 .Lkr1_exit
	s_add_u32 s28, s28, 0x100
	s_addc_u32 s29, s29, 0
	s_add_u32 s59, s59, 0x100
	s_addc_u32 s60, s60, 0
	s_cmp_eq_u32 s61, 12
	s_cselect_b64 s[30:31], -1, 0
	s_cbranch_scc0 .LBB0_332
	global_load_dwordx4 v[2:5], v[214:215], off

.Lkr1_exit:
	s_waitcnt lgkmcnt(0)
	s_add_u32 s28, s28, 0x100
	s_addc_u32 s29, s29, 0
	s_add_u32 s59, s59, 0x100
	s_addc_u32 s60, s60, 0

.LBB0_1763:
	s_ashr_i32 s23, s22, 31
	s_lshl_b64 s[24:25], s[22:23], 19
	s_add_u32 s24, s68, s24
	s_addc_u32 s25, s69, s25
	s_and_b64 s[26:27], s[6:7], exec
	s_cselect_b32 s23, s25, s47
	s_cselect_b32 s56, s24, s46
	s_ashr_i32 s21, s20, 31
	s_lshl_b64 s[26:27], s[20:21], 19
	s_add_u32 s26, s0, s26
	s_addc_u32 s27, s1, s27
	s_and_b64 s[48:49], s[6:7], exec
	s_cselect_b32 s57, s27, s31
	s_cselect_b32 s58, s26, s30
	s_lshl_b32 s21, s28, 8
	v_add_u32_e32 v6, s21, v218
	s_add_u32 s28, s46, 0x3ff80
	v_ashrrev_i32_e32 v7, 31, v6
	s_addc_u32 s29, s47, 0
	v_lshl_add_u64 v[214:215], v[6:7], 4, s[8:9]
	s_add_u32 s59, s30, 0
	v_mov_b32_e32 v6, 0
	s_addc_u32 s60, s31, 0
	s_mov_b32 s61, -4
	v_mov_b32_e32 v7, v6
	v_mov_b32_e32 v8, v6
	v_mov_b32_e32 v9, v6
	v_mov_b32_e32 v14, v6
	v_mov_b32_e32 v15, v6
	v_mov_b32_e32 v16, v6
	v_mov_b32_e32 v17, v6
	v_mov_b32_e32 v22, v6
	v_mov_b32_e32 v23, v6
	v_mov_b32_e32 v24, v6
	v_mov_b32_e32 v25, v6
	v_mov_b32_e32 v30, v6
	v_mov_b32_e32 v31, v6
	v_mov_b32_e32 v32, v6
	v_mov_b32_e32 v33, v6
	v_mov_b32_e32 v38, v6
	v_mov_b32_e32 v39, v6
	v_mov_b32_e32 v40, v6
	v_mov_b32_e32 v41, v6
	v_mov_b32_e32 v46, v6
	v_mov_b32_e32 v47, v6
	v_mov_b32_e32 v48, v6
	v_mov_b32_e32 v49, v6
	v_mov_b32_e32 v54, v6
	v_mov_b32_e32 v55, v6
	v_mov_b32_e32 v56, v6
	v_mov_b32_e32 v57, v6
	v_mov_b32_e32 v62, v6
	v_mov_b32_e32 v63, v6
	v_mov_b32_e32 v64, v6
	v_mov_b32_e32 v65, v6
	v_mov_b32_e32 v10, v6
	v_mov_b32_e32 v11, v6
	v_mov_b32_e32 v12, v6
	v_mov_b32_e32 v13, v6
	v_mov_b32_e32 v18, v6
	v_mov_b32_e32 v19, v6
	v_mov_b32_e32 v20, v6
	v_mov_b32_e32 v21, v6
	v_mov_b32_e32 v26, v6
	v_mov_b32_e32 v27, v6
	v_mov_b32_e32 v28, v6
	v_mov_b32_e32 v29, v6
	v_mov_b32_e32 v34, v6
	v_mov_b32_e32 v35, v6
	v_mov_b32_e32 v36, v6
	v_mov_b32_e32 v37, v6
	v_mov_b32_e32 v42, v6
	v_mov_b32_e32 v43, v6
	v_mov_b32_e32 v44, v6
	v_mov_b32_e32 v45, v6
	v_mov_b32_e32 v50, v6
	v_mov_b32_e32 v51, v6
	v_mov_b32_e32 v52, v6
	v_mov_b32_e32 v53, v6
	v_mov_b32_e32 v58, v6
	v_mov_b32_e32 v59, v6
	v_mov_b32_e32 v60, v6
	v_mov_b32_e32 v61, v6
	v_mov_b32_e32 v66, v6
	v_mov_b32_e32 v67, v6
	v_mov_b32_e32 v68, v6
	v_mov_b32_e32 v69, v6
	v_mov_b32_e32 v70, v6
	v_mov_b32_e32 v71, v6
	v_mov_b32_e32 v72, v6
	v_mov_b32_e32 v73, v6
	v_mov_b32_e32 v78, v6
	v_mov_b32_e32 v79, v6
	v_mov_b32_e32 v80, v6
	v_mov_b32_e32 v81, v6
	v_mov_b32_e32 v86, v6
	v_mov_b32_e32 v87, v6
	v_mov_b32_e32 v88, v6
	v_mov_b32_e32 v89, v6
	v_mov_b32_e32 v94, v6
	v_mov_b32_e32 v95, v6
	v_mov_b32_e32 v96, v6
	v_mov_b32_e32 v97, v6
	v_mov_b32_e32 v102, v6
	v_mov_b32_e32 v103, v6
	v_mov_b32_e32 v104, v6
	v_mov_b32_e32 v105, v6
	v_mov_b32_e32 v110, v6
	v_mov_b32_e32 v111, v6
	v_mov_b32_e32 v112, v6
	v_mov_b32_e32 v113, v6
	v_mov_b32_e32 v118, v6
	v_mov_b32_e32 v119, v6
	v_mov_b32_e32 v120, v6
	v_mov_b32_e32 v121, v6
	v_mov_b32_e32 v126, v6
	v_mov_b32_e32 v127, v6
	v_mov_b32_e32 v128, v6
	v_mov_b32_e32 v129, v6
	v_mov_b32_e32 v74, v6
	v_mov_b32_e32 v75, v6
	v_mov_b32_e32 v76, v6
	v_mov_b32_e32 v77, v6
	v_mov_b32_e32 v82, v6
	v_mov_b32_e32 v83, v6
	v_mov_b32_e32 v84, v6
	v_mov_b32_e32 v85, v6
	v_mov_b32_e32 v90, v6
	v_mov_b32_e32 v91, v6
	v_mov_b32_e32 v92, v6
	v_mov_b32_e32 v93, v6
	v_mov_b32_e32 v98, v6
	v_mov_b32_e32 v99, v6
	v_mov_b32_e32 v100, v6
	v_mov_b32_e32 v101, v6
	v_mov_b32_e32 v106, v6
	v_mov_b32_e32 v107, v6
	v_mov_b32_e32 v108, v6
	v_mov_b32_e32 v109, v6
	v_mov_b32_e32 v114, v6
	v_mov_b32_e32 v115, v6
	v_mov_b32_e32 v116, v6
	v_mov_b32_e32 v117, v6
	v_mov_b32_e32 v122, v6
	v_mov_b32_e32 v123, v6
	v_mov_b32_e32 v124, v6
	v_mov_b32_e32 v125, v6
	v_mov_b32_e32 v130, v6
	v_mov_b32_e32 v131, v6
	v_mov_b32_e32 v132, v6
	v_mov_b32_e32 v133, v6
	s_branch .LBB0_1766

.LBB0_1766:
	v_add_u32_e32 v146, s53, v217
	v_add_u32_e32 v162, s54, v217
	ds_read_b128 v[134:137], v146
	ds_read_b128 v[138:141], v146 offset:1024
	ds_read_b128 v[142:145], v146 offset:2048
	ds_read_b128 v[146:149], v146 offset:3072
	ds_read_b128 v[150:153], v162
	ds_read_b128 v[154:157], v162 offset:1024
	ds_read_b128 v[158:161], v162 offset:2048
	ds_read_b128 v[162:165], v162 offset:3072
	ds_read_b128 v[166:169], v220
	ds_read_b128 v[170:173], v220 offset:1024
	ds_read_b128 v[174:177], v220 offset:2048
	ds_read_b128 v[178:181], v220 offset:3072
	ds_read_b128 v[182:185], v220 offset:4096
	ds_read_b128 v[186:189], v220 offset:5120
	ds_read_b128 v[190:193], v220 offset:6144
	ds_read_b128 v[194:197], v220 offset:7168
	s_add_i32 s61, s61, 2
	s_cmp_gt_i32 s61, 13
	s_cbranch_scc1 .Lkr8_exit
	s_add_u32 s28, s28, 0x100
	s_addc_u32 s29, s29, 0
	s_add_u32 s59, s59, 0x100
	s_addc_u32 s60, s60, 0
	s_cmp_eq_u32 s61, 12
	s_cselect_b64 s[30:31], -1, 0
	s_cbranch_scc0 .LBB0_1768
	global_load_dwordx4 v[2:5], v[214:215], off
.LBB0_1768:
	s_add_u32 s48, s28, 0xfffc0080
	s_addc_u32 s49, s29, -1
	s_and_b64 s[46:47], s[30:31], exec
	s_cselect_b32 s49, s23, s49
	s_cselect_b32 s48, s56, s48
	s_cselect_b32 s47, s57, s60
	s_cselect_b32 s46, s58, s59
	s_add_i32 m0, s40, 0xc000
	s_nop 0
	global_load_lds_dwordx4 v206, s[28:29]
	s_add_i32 m0, s40, 0xe000
	s_nop 0
	global_load_lds_dwordx4 v208, s[28:29]
	s_waitcnt vmcnt(8) lgkmcnt(0)
	s_barrier
	v_mfma_f32_16x16x32_bf16 v[130:133], v[134:137], v[166:169], v[130:133]
	v_mfma_f32_16x16x32_bf16 v[122:125], v[142:145], v[166:169], v[122:125]
	v_mfma_f32_16x16x32_bf16 v[114:117], v[134:137], v[174:177], v[114:117]
	v_mfma_f32_16x16x32_bf16 v[106:109], v[142:145], v[174:177], v[106:109]
	v_mfma_f32_16x16x32_bf16 v[98:101], v[134:137], v[182:185], v[98:101]
	v_mfma_f32_16x16x32_bf16 v[90:93], v[142:145], v[182:185], v[90:93]
	v_mfma_f32_16x16x32_bf16 v[82:85], v[134:137], v[190:193], v[82:85]
	v_mfma_f32_16x16x32_bf16 v[74:77], v[142:145], v[190:193], v[74:77]
	v_mfma_f32_16x16x32_bf16 v[130:133], v[138:141], v[170:173], v[130:133]
	v_mfma_f32_16x16x32_bf16 v[122:125], v[146:149], v[170:173], v[122:125]
	v_mfma_f32_16x16x32_bf16 v[114:117], v[138:141], v[178:181], v[114:117]
	v_mfma_f32_16x16x32_bf16 v[106:109], v[146:149], v[178:181], v[106:109]
	v_mfma_f32_16x16x32_bf16 v[98:101], v[138:141], v[186:189], v[98:101]
	v_mfma_f32_16x16x32_bf16 v[90:93], v[146:149], v[186:189], v[90:93]
	v_mfma_f32_16x16x32_bf16 v[82:85], v[138:141], v[194:197], v[82:85]
	v_mfma_f32_16x16x32_bf16 v[74:77], v[146:149], v[194:197], v[74:77]
	v_mfma_f32_16x16x32_bf16 v[126:129], v[150:153], v[166:169], v[126:129]
	v_mfma_f32_16x16x32_bf16 v[118:121], v[158:161], v[166:169], v[118:121]
	v_mfma_f32_16x16x32_bf16 v[110:113], v[150:153], v[174:177], v[110:113]
	v_mfma_f32_16x16x32_bf16 v[102:105], v[158:161], v[174:177], v[102:105]
	v_mfma_f32_16x16x32_bf16 v[94:97], v[150:153], v[182:185], v[94:97]
	v_mfma_f32_16x16x32_bf16 v[86:89], v[158:161], v[182:185], v[86:89]
	v_mfma_f32_16x16x32_bf16 v[78:81], v[150:153], v[190:193], v[78:81]
	v_mfma_f32_16x16x32_bf16 v[70:73], v[158:161], v[190:193], v[70:73]
	v_mfma_f32_16x16x32_bf16 v[126:129], v[154:157], v[170:173], v[126:129]
	v_mfma_f32_16x16x32_bf16 v[118:121], v[162:165], v[170:173], v[118:121]
	v_mfma_f32_16x16x32_bf16 v[110:113], v[154:157], v[178:181], v[110:113]
	v_mfma_f32_16x16x32_bf16 v[102:105], v[162:165], v[178:181], v[102:105]
	v_mfma_f32_16x16x32_bf16 v[94:97], v[154:157], v[186:189], v[94:97]
	v_mfma_f32_16x16x32_bf16 v[86:89], v[162:165], v[186:189], v[86:89]
	v_mfma_f32_16x16x32_bf16 v[78:81], v[154:157], v[194:197], v[78:81]
	v_mfma_f32_16x16x32_bf16 v[70:73], v[162:165], v[194:197], v[70:73]
	s_barrier
	ds_read_b128 v[166:169], v220 offset:16384
	ds_read_b128 v[170:173], v220 offset:17408
	ds_read_b128 v[174:177], v220 offset:18432
	ds_read_b128 v[178:181], v220 offset:19456
	ds_read_b128 v[182:185], v220 offset:20480
	ds_read_b128 v[186:189], v220 offset:21504
	ds_read_b128 v[190:193], v220 offset:22528
	ds_read_b128 v[194:197], v220 offset:23552
	s_add_i32 s62, s53, s12
	s_add_u32 s98, s46, s16
	s_addc_u32 s99, s47, s17
	s_mov_b32 m0, s62
	s_nop 0
	global_load_lds_dwordx4 v202, s[46:47]
	s_add_i32 m0, s62, 0x2000
	s_add_u32 s62, s46, 0x40000
	s_addc_u32 s63, s47, 0
	s_add_i32 s64, s54, s12
	global_load_lds_dwordx4 v198, s[46:47]
	s_mov_b32 m0, s64
	s_nop 0
	global_load_lds_dwordx4 v202, s[62:63]
	s_add_i32 m0, s64, 0x2000
	s_nop 0
	global_load_lds_dwordx4 v198, s[62:63]
	s_add_u32 s100, s48, s16
	s_addc_u32 s101, s49, s17
	s_mov_b32 m0, s40
	s_nop 0
	global_load_lds_dwordx4 v204, s[48:49]
	s_mov_b32 m0, s41
	s_nop 0
	global_load_lds_dwordx4 v200, s[48:49]
	s_waitcnt vmcnt(8) lgkmcnt(0)
	s_barrier
	v_mfma_f32_16x16x32_bf16 v[66:69], v[134:137], v[166:169], v[66:69]
	v_mfma_f32_16x16x32_bf16 v[58:61], v[142:145], v[166:169], v[58:61]
	v_mfma_f32_16x16x32_bf16 v[50:53], v[134:137], v[174:177], v[50:53]
	v_mfma_f32_16x16x32_bf16 v[42:45], v[142:145], v[174:177], v[42:45]
	v_mfma_f32_16x16x32_bf16 v[34:37], v[134:137], v[182:185], v[34:37]
	v_mfma_f32_16x16x32_bf16 v[26:29], v[142:145], v[182:185], v[26:29]
	v_mfma_f32_16x16x32_bf16 v[18:21], v[134:137], v[190:193], v[18:21]
	v_mfma_f32_16x16x32_bf16 v[10:13], v[142:145], v[190:193], v[10:13]
	v_mfma_f32_16x16x32_bf16 v[66:69], v[138:141], v[170:173], v[66:69]
	v_mfma_f32_16x16x32_bf16 v[58:61], v[146:149], v[170:173], v[58:61]
	v_mfma_f32_16x16x32_bf16 v[50:53], v[138:141], v[178:181], v[50:53]
	v_mfma_f32_16x16x32_bf16 v[42:45], v[146:149], v[178:181], v[42:45]
	v_mfma_f32_16x16x32_bf16 v[34:37], v[138:141], v[186:189], v[34:37]
	v_mfma_f32_16x16x32_bf16 v[26:29], v[146:149], v[186:189], v[26:29]
	v_mfma_f32_16x16x32_bf16 v[18:21], v[138:141], v[194:197], v[18:21]
	v_mfma_f32_16x16x32_bf16 v[10:13], v[146:149], v[194:197], v[10:13]
	v_mfma_f32_16x16x32_bf16 v[62:65], v[150:153], v[166:169], v[62:65]
	v_mfma_f32_16x16x32_bf16 v[54:57], v[158:161], v[166:169], v[54:57]
	v_mfma_f32_16x16x32_bf16 v[46:49], v[150:153], v[174:177], v[46:49]
	v_mfma_f32_16x16x32_bf16 v[38:41], v[158:161], v[174:177], v[38:41]
	v_mfma_f32_16x16x32_bf16 v[30:33], v[150:153], v[182:185], v[30:33]
	v_mfma_f32_16x16x32_bf16 v[22:25], v[158:161], v[182:185], v[22:25]
	v_mfma_f32_16x16x32_bf16 v[14:17], v[150:153], v[190:193], v[14:17]
	v_mfma_f32_16x16x32_bf16 v[6:9], v[158:161], v[190:193], v[6:9]
	v_mfma_f32_16x16x32_bf16 v[62:65], v[154:157], v[170:173], v[62:65]
	v_mfma_f32_16x16x32_bf16 v[54:57], v[162:165], v[170:173], v[54:57]
	v_mfma_f32_16x16x32_bf16 v[46:49], v[154:157], v[178:181], v[46:49]
	v_mfma_f32_16x16x32_bf16 v[38:41], v[162:165], v[178:181], v[38:41]
	v_mfma_f32_16x16x32_bf16 v[30:33], v[154:157], v[186:189], v[30:33]
	v_mfma_f32_16x16x32_bf16 v[22:25], v[162:165], v[186:189], v[22:25]
	v_mfma_f32_16x16x32_bf16 v[14:17], v[154:157], v[194:197], v[14:17]
	v_mfma_f32_16x16x32_bf16 v[6:9], v[162:165], v[194:197], v[6:9]
	s_barrier
	ds_read_b128 v[166:169], v220 offset:32768
	ds_read_b128 v[170:173], v220 offset:33792
	ds_read_b128 v[174:177], v220 offset:34816
	ds_read_b128 v[178:181], v220 offset:35840
	ds_read_b128 v[182:185], v220 offset:36864
	ds_read_b128 v[186:189], v220 offset:37888
	ds_read_b128 v[190:193], v220 offset:38912
	ds_read_b128 v[194:197], v220 offset:39936
	v_add_u32_e32 v134, 0x18000, v217
	v_add_u32_e32 v146, 0x1c000, v217
	ds_read_b128 v[150:153], v134
	ds_read_b128 v[154:157], v134 offset:1024
	ds_read_b128 v[158:161], v134 offset:2048
	ds_read_b128 v[162:165], v134 offset:3072
	ds_read_b128 v[134:137], v146
	ds_read_b128 v[138:141], v146 offset:1024
	ds_read_b128 v[142:145], v146 offset:2048
	ds_read_b128 v[146:149], v146 offset:3072
	s_add_i32 s62, 0, 0x18000
	s_add_i32 s63, 0, 0x1c000
	s_add_u32 s48, s48, 0x40000
	s_addc_u32 s49, s49, 0
	s_mov_b32 m0, s42
	s_nop 0
	global_load_lds_dwordx4 v204, s[48:49]
	s_mov_b32 m0, s43
	s_nop 0
	global_load_lds_dwordx4 v200, s[48:49]
	s_waitcnt vmcnt(8) lgkmcnt(0)
	s_barrier
	v_mfma_f32_16x16x32_bf16 v[130:133], v[150:153], v[166:169], v[130:133]
	v_mfma_f32_16x16x32_bf16 v[122:125], v[158:161], v[166:169], v[122:125]
	v_mfma_f32_16x16x32_bf16 v[114:117], v[150:153], v[174:177], v[114:117]
	v_mfma_f32_16x16x32_bf16 v[106:109], v[158:161], v[174:177], v[106:109]
	v_mfma_f32_16x16x32_bf16 v[98:101], v[150:153], v[182:185], v[98:101]
	v_mfma_f32_16x16x32_bf16 v[90:93], v[158:161], v[182:185], v[90:93]
	v_mfma_f32_16x16x32_bf16 v[82:85], v[150:153], v[190:193], v[82:85]
	v_mfma_f32_16x16x32_bf16 v[74:77], v[158:161], v[190:193], v[74:77]
	v_mfma_f32_16x16x32_bf16 v[130:133], v[154:157], v[170:173], v[130:133]
	v_mfma_f32_16x16x32_bf16 v[122:125], v[162:165], v[170:173], v[122:125]
	v_mfma_f32_16x16x32_bf16 v[114:117], v[154:157], v[178:181], v[114:117]
	v_mfma_f32_16x16x32_bf16 v[106:109], v[162:165], v[178:181], v[106:109]
	v_mfma_f32_16x16x32_bf16 v[98:101], v[154:157], v[186:189], v[98:101]
	v_mfma_f32_16x16x32_bf16 v[90:93], v[162:165], v[186:189], v[90:93]
	v_mfma_f32_16x16x32_bf16 v[82:85], v[154:157], v[194:197], v[82:85]
	v_mfma_f32_16x16x32_bf16 v[74:77], v[162:165], v[194:197], v[74:77]
	v_mfma_f32_16x16x32_bf16 v[126:129], v[134:137], v[166:169], v[126:129]
	v_mfma_f32_16x16x32_bf16 v[118:121], v[142:145], v[166:169], v[118:121]
	v_mfma_f32_16x16x32_bf16 v[110:113], v[134:137], v[174:177], v[110:113]
	v_mfma_f32_16x16x32_bf16 v[102:105], v[142:145], v[174:177], v[102:105]
	v_mfma_f32_16x16x32_bf16 v[94:97], v[134:137], v[182:185], v[94:97]
	v_mfma_f32_16x16x32_bf16 v[86:89], v[142:145], v[182:185], v[86:89]
	v_mfma_f32_16x16x32_bf16 v[78:81], v[134:137], v[190:193], v[78:81]
	v_mfma_f32_16x16x32_bf16 v[70:73], v[142:145], v[190:193], v[70:73]
	v_mfma_f32_16x16x32_bf16 v[126:129], v[138:141], v[170:173], v[126:129]
	v_mfma_f32_16x16x32_bf16 v[118:121], v[146:149], v[170:173], v[118:121]
	v_mfma_f32_16x16x32_bf16 v[110:113], v[138:141], v[178:181], v[110:113]
	v_mfma_f32_16x16x32_bf16 v[102:105], v[146:149], v[178:181], v[102:105]
	v_mfma_f32_16x16x32_bf16 v[94:97], v[138:141], v[186:189], v[94:97]
	v_mfma_f32_16x16x32_bf16 v[86:89], v[146:149], v[186:189], v[86:89]
	v_mfma_f32_16x16x32_bf16 v[78:81], v[138:141], v[194:197], v[78:81]
	v_mfma_f32_16x16x32_bf16 v[70:73], v[146:149], v[194:197], v[70:73]
	s_barrier
	ds_read_b128 v[190:193], v220 offset:49152
	ds_read_b128 v[194:197], v220 offset:50176
	ds_read_b128 v[182:185], v220 offset:51200
	ds_read_b128 v[186:189], v220 offset:52224
	ds_read_b128 v[174:177], v220 offset:53248
	ds_read_b128 v[178:181], v220 offset:54272
	ds_read_b128 v[166:169], v220 offset:55296
	ds_read_b128 v[170:173], v220 offset:56320
	s_add_i32 s48, s62, s12
	s_mov_b32 m0, s48
	s_nop 0
	global_load_lds_dwordx4 v202, s[98:99]
	s_add_i32 m0, s48, 0x2000
	s_add_u32 s46, s46, 0x40080
	s_addc_u32 s47, s47, 0
	s_add_i32 s48, s63, s12
	global_load_lds_dwordx4 v198, s[98:99]
	s_mov_b32 m0, s48
	s_andn2_b64 vcc, exec, s[30:31]
	global_load_lds_dwordx4 v202, s[46:47]
	s_add_i32 m0, s48, 0x2000
	s_nop 0
	global_load_lds_dwordx4 v198, s[46:47]
	s_mov_b32 m0, s51
	s_nop 0
	global_load_lds_dwordx4 v204, s[100:101]
	s_mov_b32 m0, s52
	s_nop 0
	global_load_lds_dwordx4 v200, s[100:101]
	s_waitcnt vmcnt(8)
	s_cbranch_vccnz .LBB0_1765
	s_and_saveexec_b64 s[30:31], s[4:5]
	s_cbranch_execz .LBB0_1764
	v_mov_b32_e32 v222, v3
	v_mov_b32_e32 v223, v4
	v_mov_b32_e32 v224, v2
	v_mov_b32_e32 v225, v5
	v_pk_add_f32 v[222:223], v[222:223], v[224:225]
	s_nop 0
	v_add_f32_e32 v222, v222, v223
	v_fmamk_f32 v222, v222, 0x3a800000, v221
	ds_write_b32 v219, v222
	s_branch .LBB0_1764
